# P1 epilogue rstd loads hoisted to unit entry + P10 slab prologue DMAs hoisted above main epilogue
# baseline (speedup 1.0000x reference)
.LBB0_211:
	s_ashr_i32 s41, s40, 31
	v_cmp_lt_i64_e32 vcc, s[8:9], v[160:161]
	s_lshl_b64 s[8:9], s[40:41], 19
	s_add_u32 s42, s47, s8
	s_addc_u32 s43, s48, s9
	s_and_b64 s[8:9], vcc, exec
	s_cselect_b32 s1, s43, s3
	s_cselect_b32 s33, s42, s2
	s_ashr_i32 s39, s38, 31
	s_lshl_b64 s[8:9], s[38:39], 19
	s_add_u32 s44, s94, s8
	s_addc_u32 s45, s95, s9
	s_and_b64 s[8:9], vcc, exec
	s_cselect_b32 s39, s45, s7
	s_cselect_b32 s41, s44, s6
	s_add_u32 s2, s2, 0x40080
	s_addc_u32 s3, s3, 0
	s_add_u32 s71, s6, 0x100
	s_addc_u32 s72, s7, 0
	s_mov_b32 s73, -2
	v_add_u32_e32 v182, s55, v167
	v_lshl_add_u32 v180, s0, 8, v182
	v_ashrrev_i32_e32 v181, 31, v180
	v_lshl_add_u64 v[130:131], v[180:181], 2, s[62:63]
	global_load_dword v178, v[130:131], off
	global_load_dword v176, v[130:131], off offset:64
	global_load_dword v174, v[130:131], off offset:128
	global_load_dword v172, v[130:131], off offset:192
	global_load_dword v170, v[130:131], off offset:512
	global_load_dword v168, v[130:131], off offset:576
	global_load_dword v166, v[130:131], off offset:640
	global_load_dword v164, v[130:131], off offset:704

.Lpeel_p1_exit:
	v_mov_b32_e32 v154, v167
	v_mov_b32_e32 v194, v169
	s_cmp_lt_i32 s70, 16
	v_add_u32_e32 v182, s55, v154
	v_lshl_add_u32 v180, s0, 8, v182
	v_ashrrev_i32_e32 v181, 31, v180
	s_mov_b64 s[2:3], -1
	s_cbranch_scc0 .LBB0_226
	v_lshl_add_u32 v183, v194, 2, s58
	v_lshl_add_u32 v186, s70, 6, v183
	v_ashrrev_i32_e32 v187, 31, v186
	v_readlane_b32 s8, v248, 18
	v_lshlrev_b64 v[184:185], 2, v[186:187]
	v_readlane_b32 s20, v248, 30
	v_readlane_b32 s21, v248, 31
	v_lshl_add_u64 v[134:135], s[34:35], 0, v[184:185]
	s_cmp_lg_u32 s0, 64
	v_lshl_add_u64 v[130:131], s[20:21], 0, v[184:185]
	global_load_dwordx4 v[130:133], v[130:131], off
	s_nop 0
	global_load_dwordx4 v[138:141], v[134:135], off
	v_lshl_add_u64 v[134:135], s[36:37], 0, v[184:185]
	global_load_dwordx4 v[134:137], v[134:135], off
	v_readlane_b32 s9, v248, 19
	v_readlane_b32 s10, v248, 20
	v_readlane_b32 s11, v248, 21
	v_readlane_b32 s12, v248, 22
	v_readlane_b32 s13, v248, 23
	v_readlane_b32 s14, v248, 24
	v_readlane_b32 s15, v248, 25
	v_readlane_b32 s16, v248, 26
	v_readlane_b32 s17, v248, 27
	v_readlane_b32 s18, v248, 28
	v_readlane_b32 s19, v248, 29
	v_readlane_b32 s22, v248, 32
	v_readlane_b32 s23, v248, 33
	s_cbranch_scc0 .LBB0_223
	v_cmp_lt_i32_e32 vcc, 13, v154
	v_lshlrev_b32_e32 v192, 2, v183
	v_mul_f32_e32 v188, v164, v164
	v_pk_mul_f32 v[190:191], v[14:15], v[6:7]
	s_and_saveexec_b64 s[2:3], vcc
	s_cbranch_execz .LBB0_218
	v_pk_mul_f32 v[144:145], v[80:81], v[72:73]
	v_pk_mul_f32 v[142:143], v[78:79], v[70:71]
	v_mul_f32_e32 v196, v172, v172
	v_add_lshl_u32 v193, s59, v154, 8
	s_add_i32 s1, 0, 0x20010
	v_pk_mul_f32 v[142:143], v[142:143], v[196:197] op_sel_hi:[1,0]
	v_pk_mul_f32 v[144:145], v[144:145], v[196:197] op_sel_hi:[1,0]
	v_add3_u32 v195, s1, v193, v192
	v_readlane_b32 s6, v248, 43
	ds_write_b128 v195, v[142:145]
	v_pk_mul_f32 v[144:145], v[16:17], v[8:9]
	v_readlane_b32 s7, v248, 44
	v_pk_mul_f32 v[142:143], v[190:191], v[188:189] op_sel_hi:[1,0]
	v_pk_mul_f32 v[144:145], v[144:145], v[188:189] op_sel_hi:[1,0]
	v_add3_u32 v193, s68, v193, v192
	s_andn2_b64 vcc, exec, s[6:7]
	ds_write_b128 v193, v[142:145]
	s_cbranch_vccnz .LBB0_218
	s_lshl_b32 s1, s0, 1
	v_add3_u32 v196, s1, -14, v154
	v_ashrrev_i32_e32 v197, 31, v196
	v_readlane_b32 s6, v248, 47
	v_lshlrev_b64 v[196:197], 12, v[196:197]
	v_readlane_b32 s7, v248, 48
	s_nop 1
	v_lshl_add_u64 v[196:197], s[6:7], 0, v[196:197]
	v_lshl_add_u64 v[196:197], v[186:187], 2, v[196:197]
	global_store_dwordx4 v[196:197], v[142:145], off

.LBB0_222:
	v_cmp_lt_i32_e64 s[2:3], 0, v154
	v_cmp_lt_i32_e64 s[0:1], 1, v154
	v_lshlrev_b64 v[192:193], 12, v[180:181]
	v_and_b32_e32 v154, 1, v194
	v_and_b32_e32 v181, 64, v189
	v_cmp_eq_u32_e32 vcc, 0, v154
	v_xor_b32_e32 v154, 16, v189
	v_add_u32_e32 v181, 64, v181
	v_cmp_lt_i32_e64 s[8:9], v154, v181
	v_lshl_add_u64 v[192:193], s[30:31], 0, v[192:193]
	v_bfe_i32 v199, v194, 0, 1
	v_cndmask_b32_e64 v154, v189, v154, s[8:9]
	v_lshl_add_u64 v[192:193], v[186:187], 1, v[192:193]
	v_lshlrev_b32_e32 v181, 2, v154
	v_and_b32_e32 v154, 0x7f8, v199
	v_lshl_add_u64 v[192:193], v[192:193], 0, v[154:155]
	v_mul_f32_e32 v154, v178, v178
	v_pk_mul_f32 v[202:203], v[122:123], v[114:115]
	v_pk_mul_f32 v[200:201], v[124:125], v[116:117]
	v_pk_mul_f32 v[202:203], v[202:203], v[154:155] op_sel_hi:[1,0]
	v_pk_mul_f32 v[204:205], v[126:127], v[178:179] op_sel_hi:[1,0]
	s_mov_b32 s8, 0x10000
	v_mov_b32_dpp v207, v202 row_ror:2 row_mask:0xf bank_mask:0xf bound_ctrl:1
	v_mov_b32_dpp v209, v203 row_ror:2 row_mask:0xf bank_mask:0xf bound_ctrl:1
	v_mov_b32_dpp v206, v202 row_ror:1 row_mask:0xf bank_mask:0xf bound_ctrl:1
	v_mov_b32_dpp v208, v203 row_ror:1 row_mask:0xf bank_mask:0xf bound_ctrl:1
	v_cndmask_b32_e64 v199, v198, v209, s[0:1]
	v_cndmask_b32_e64 v198, v197, v207, s[0:1]
	v_cndmask_b32_e64 v143, v143, v208, s[2:3]
	v_cndmask_b32_e64 v142, v142, v206, s[2:3]
	s_waitcnt vmcnt(0)
	v_pk_mul_f32 v[198:199], v[130:131], v[198:199]
	s_nop 0
	v_pk_fma_f32 v[142:143], v[138:139], v[142:143], v[198:199]
	v_pk_mul_f32 v[198:199], v[200:201], v[154:155] op_sel_hi:[1,0]
	v_pk_fma_f32 v[142:143], v[202:203], v[134:135], v[142:143]
	v_pk_mul_f32 v[200:201], v[128:129], v[178:179] op_sel_hi:[1,0]
	v_pk_mul_f32 v[142:143], v[204:205], v[142:143]
	v_mov_b32_dpp v204, v198 row_ror:2 row_mask:0xf bank_mask:0xf bound_ctrl:1
	v_mov_b32_dpp v210, v199 row_ror:2 row_mask:0xf bank_mask:0xf bound_ctrl:1
	v_mov_b32_dpp v154, v198 row_ror:1 row_mask:0xf bank_mask:0xf bound_ctrl:1
	v_mov_b32_dpp v205, v199 row_ror:1 row_mask:0xf bank_mask:0xf bound_ctrl:1
	v_cndmask_b32_e64 v197, v196, v210, s[0:1]
	v_cndmask_b32_e64 v196, v195, v204, s[0:1]
	v_cndmask_b32_e64 v145, v145, v205, s[2:3]
	v_cndmask_b32_e64 v144, v144, v154, s[2:3]
	v_pk_mul_f32 v[196:197], v[132:133], v[196:197]
	v_cvt_pk_bf16_f32 v142, v142, v143
	v_pk_fma_f32 v[144:145], v[140:141], v[144:145], v[196:197]
	v_pk_mul_f32 v[196:197], v[108:109], v[178:179] op_sel_hi:[1,0]
	v_pk_fma_f32 v[144:145], v[198:199], v[136:137], v[144:145]
	v_pk_mul_f32 v[198:199], v[106:107], v[178:179] op_sel_hi:[1,0]
	v_pk_mul_f32 v[144:145], v[200:201], v[144:145]
	v_cvt_pk_bf16_f32 v195, v198, v199
	v_cvt_pk_bf16_f32 v196, v196, v197
	v_cvt_pk_bf16_f32 v143, v144, v145
	v_cndmask_b32_e32 v144, v196, v143, vcc
	v_cndmask_b32_e32 v145, v195, v142, vcc
	ds_bpermute_b32 v197, v181, v145
	ds_bpermute_b32 v198, v181, v144
	v_pk_mul_f32 v[202:203], v[118:119], v[176:177] op_sel_hi:[1,0]
	s_waitcnt lgkmcnt(0)
	v_cndmask_b32_e32 v144, v142, v197, vcc
	v_cndmask_b32_e32 v145, v143, v198, vcc
	v_cndmask_b32_e32 v142, v197, v195, vcc
	v_cndmask_b32_e32 v143, v198, v196, vcc
	global_store_dwordx4 v[192:193], v[142:145], off
	v_pk_mul_f32 v[196:197], v[110:111], v[98:99]
	s_nop 0
	v_mul_f32_e32 v142, v176, v176
	v_pk_mul_f32 v[196:197], v[196:197], v[142:143] op_sel_hi:[1,0]
	v_pk_mul_f32 v[144:145], v[112:113], v[100:101]
	s_nop 0
	v_mov_b32_dpp v211, v196 row_ror:2 row_mask:0xf bank_mask:0xf bound_ctrl:1
	v_mov_b32_dpp v213, v197 row_ror:2 row_mask:0xf bank_mask:0xf bound_ctrl:1
	v_mov_b32_dpp v195, v196 row_ror:1 row_mask:0xf bank_mask:0xf bound_ctrl:1
	v_mov_b32_dpp v212, v197 row_ror:1 row_mask:0xf bank_mask:0xf bound_ctrl:1
	v_cndmask_b32_e64 v201, v209, v213, s[0:1]
	v_cndmask_b32_e64 v200, v207, v211, s[0:1]
	v_cndmask_b32_e64 v199, v208, v212, s[2:3]
	v_cndmask_b32_e64 v198, v206, v195, s[2:3]
	v_pk_mul_f32 v[200:201], v[130:131], v[200:201]
	v_pk_mul_f32 v[142:143], v[144:145], v[142:143] op_sel_hi:[1,0]
	v_pk_fma_f32 v[198:199], v[138:139], v[198:199], v[200:201]
	v_pk_mul_f32 v[200:201], v[120:121], v[176:177] op_sel_hi:[1,0]
	v_mov_b32_dpp v207, v142 row_ror:2 row_mask:0xf bank_mask:0xf bound_ctrl:1
	v_mov_b32_dpp v209, v143 row_ror:2 row_mask:0xf bank_mask:0xf bound_ctrl:1
	v_pk_fma_f32 v[196:197], v[196:197], v[134:135], v[198:199]
	v_mov_b32_dpp v206, v142 row_ror:1 row_mask:0xf bank_mask:0xf bound_ctrl:1
	v_mov_b32_dpp v208, v143 row_ror:1 row_mask:0xf bank_mask:0xf bound_ctrl:1
	v_cndmask_b32_e64 v199, v210, v209, s[0:1]
	v_cndmask_b32_e64 v198, v204, v207, s[0:1]
	v_cndmask_b32_e64 v145, v205, v208, s[2:3]
	v_cndmask_b32_e64 v144, v154, v206, s[2:3]
	v_pk_mul_f32 v[198:199], v[132:133], v[198:199]
	v_pk_mul_f32 v[196:197], v[202:203], v[196:197]
	v_pk_fma_f32 v[144:145], v[140:141], v[144:145], v[198:199]
	v_pk_mul_f32 v[198:199], v[90:91], v[176:177] op_sel_hi:[1,0]
	v_pk_fma_f32 v[142:143], v[142:143], v[136:137], v[144:145]
	v_pk_mul_f32 v[144:145], v[92:93], v[176:177] op_sel_hi:[1,0]
	v_pk_mul_f32 v[142:143], v[200:201], v[142:143]
	v_cvt_pk_bf16_f32 v154, v198, v199
	v_cvt_pk_bf16_f32 v198, v144, v145
	v_cvt_pk_bf16_f32 v144, v196, v197
	v_cvt_pk_bf16_f32 v142, v142, v143
	v_cndmask_b32_e32 v143, v198, v142, vcc
	v_cndmask_b32_e32 v145, v154, v144, vcc
	ds_bpermute_b32 v196, v181, v145
	ds_bpermute_b32 v143, v181, v143
	v_pk_mul_f32 v[202:203], v[102:103], v[174:175] op_sel_hi:[1,0]
	s_waitcnt lgkmcnt(1)
	v_cndmask_b32_e32 v144, v144, v196, vcc
	s_waitcnt lgkmcnt(0)
	v_cndmask_b32_e32 v145, v142, v143, vcc
	v_cndmask_b32_e32 v142, v196, v154, vcc
	v_add_co_u32_e64 v196, s[8:9], s8, v192
	v_cndmask_b32_e32 v143, v143, v198, vcc
	s_nop 0
	v_addc_co_u32_e64 v197, s[8:9], 0, v193, s[8:9]
	global_store_dwordx4 v[196:197], v[142:145], off
	v_pk_mul_f32 v[196:197], v[94:95], v[82:83]
	s_mov_b32 s8, 0x20000
	v_mul_f32_e32 v142, v174, v174
	v_pk_mul_f32 v[196:197], v[196:197], v[142:143] op_sel_hi:[1,0]
	v_pk_mul_f32 v[144:145], v[96:97], v[84:85]
	s_nop 0
	v_mov_b32_dpp v204, v196 row_ror:2 row_mask:0xf bank_mask:0xf bound_ctrl:1
	v_mov_b32_dpp v210, v197 row_ror:2 row_mask:0xf bank_mask:0xf bound_ctrl:1
	v_mov_b32_dpp v154, v196 row_ror:1 row_mask:0xf bank_mask:0xf bound_ctrl:1
	v_mov_b32_dpp v205, v197 row_ror:1 row_mask:0xf bank_mask:0xf bound_ctrl:1
	v_cndmask_b32_e64 v201, v213, v210, s[0:1]
	v_cndmask_b32_e64 v200, v211, v204, s[0:1]
	v_cndmask_b32_e64 v199, v212, v205, s[2:3]
	v_cndmask_b32_e64 v198, v195, v154, s[2:3]
	v_pk_mul_f32 v[200:201], v[130:131], v[200:201]
	v_pk_mul_f32 v[142:143], v[144:145], v[142:143] op_sel_hi:[1,0]
	v_pk_fma_f32 v[198:199], v[138:139], v[198:199], v[200:201]
	v_pk_mul_f32 v[200:201], v[104:105], v[174:175] op_sel_hi:[1,0]
	v_mov_b32_dpp v211, v142 row_ror:2 row_mask:0xf bank_mask:0xf bound_ctrl:1
	v_mov_b32_dpp v213, v143 row_ror:2 row_mask:0xf bank_mask:0xf bound_ctrl:1
	v_pk_fma_f32 v[196:197], v[196:197], v[134:135], v[198:199]
	v_mov_b32_dpp v195, v142 row_ror:1 row_mask:0xf bank_mask:0xf bound_ctrl:1
	v_mov_b32_dpp v212, v143 row_ror:1 row_mask:0xf bank_mask:0xf bound_ctrl:1
	v_cndmask_b32_e64 v199, v209, v213, s[0:1]
	v_cndmask_b32_e64 v198, v207, v211, s[0:1]
	v_cndmask_b32_e64 v145, v208, v212, s[2:3]
	v_cndmask_b32_e64 v144, v206, v195, s[2:3]
	v_pk_mul_f32 v[198:199], v[132:133], v[198:199]
	v_pk_mul_f32 v[196:197], v[202:203], v[196:197]
	v_pk_fma_f32 v[144:145], v[140:141], v[144:145], v[198:199]
	v_pk_mul_f32 v[198:199], v[74:75], v[174:175] op_sel_hi:[1,0]
	v_pk_fma_f32 v[142:143], v[142:143], v[136:137], v[144:145]
	v_pk_mul_f32 v[144:145], v[76:77], v[174:175] op_sel_hi:[1,0]
	v_pk_mul_f32 v[142:143], v[200:201], v[142:143]
	v_cvt_pk_bf16_f32 v198, v198, v199
	v_cvt_pk_bf16_f32 v199, v144, v145
	v_cvt_pk_bf16_f32 v144, v196, v197
	v_cvt_pk_bf16_f32 v142, v142, v143
	v_cndmask_b32_e32 v143, v199, v142, vcc
	v_cndmask_b32_e32 v145, v198, v144, vcc
	ds_bpermute_b32 v196, v181, v145
	ds_bpermute_b32 v143, v181, v143
	v_pk_mul_f32 v[202:203], v[86:87], v[172:173] op_sel_hi:[1,0]
	s_waitcnt lgkmcnt(1)
	v_cndmask_b32_e32 v144, v144, v196, vcc
	s_waitcnt lgkmcnt(0)
	v_cndmask_b32_e32 v145, v142, v143, vcc
	v_cndmask_b32_e32 v142, v196, v198, vcc
	v_add_co_u32_e64 v196, s[8:9], s8, v192
	v_cndmask_b32_e32 v143, v143, v199, vcc
	s_nop 0
	v_addc_co_u32_e64 v197, s[8:9], 0, v193, s[8:9]
	global_store_dwordx4 v[196:197], v[142:145], off
	v_pk_mul_f32 v[196:197], v[78:79], v[70:71]
	s_mov_b32 s8, 0x30000
	v_mul_f32_e32 v142, v172, v172
	v_pk_mul_f32 v[196:197], v[196:197], v[142:143] op_sel_hi:[1,0]
	v_pk_mul_f32 v[144:145], v[80:81], v[72:73]
	s_nop 0
	v_mov_b32_dpp v200, v196 row_ror:2 row_mask:0xf bank_mask:0xf bound_ctrl:1
	v_mov_b32_dpp v201, v197 row_ror:2 row_mask:0xf bank_mask:0xf bound_ctrl:1
	v_mov_b32_dpp v143, v196 row_ror:1 row_mask:0xf bank_mask:0xf bound_ctrl:1
	v_mov_b32_dpp v198, v197 row_ror:1 row_mask:0xf bank_mask:0xf bound_ctrl:1
	v_cndmask_b32_e64 v201, v210, v201, s[0:1]
	v_cndmask_b32_e64 v200, v204, v200, s[0:1]
	v_cndmask_b32_e64 v199, v205, v198, s[2:3]
	v_cndmask_b32_e64 v198, v154, v143, s[2:3]
	v_pk_mul_f32 v[200:201], v[130:131], v[200:201]
	v_pk_mul_f32 v[142:143], v[144:145], v[142:143] op_sel_hi:[1,0]
	v_pk_fma_f32 v[198:199], v[138:139], v[198:199], v[200:201]
	v_pk_mul_f32 v[200:201], v[88:89], v[172:173] op_sel_hi:[1,0]
	v_pk_fma_f32 v[196:197], v[196:197], v[134:135], v[198:199]
	v_mov_b32_dpp v154, v142 row_ror:2 row_mask:0xf bank_mask:0xf bound_ctrl:1
	v_mov_b32_dpp v198, v143 row_ror:2 row_mask:0xf bank_mask:0xf bound_ctrl:1
	v_mov_b32_dpp v144, v142 row_ror:1 row_mask:0xf bank_mask:0xf bound_ctrl:1
	v_mov_b32_dpp v145, v143 row_ror:1 row_mask:0xf bank_mask:0xf bound_ctrl:1
	v_cndmask_b32_e64 v199, v213, v198, s[0:1]
	v_cndmask_b32_e64 v198, v211, v154, s[0:1]
	v_cndmask_b32_e64 v145, v212, v145, s[2:3]
	v_cndmask_b32_e64 v144, v195, v144, s[2:3]
	v_pk_mul_f32 v[198:199], v[132:133], v[198:199]
	v_pk_mul_f32 v[196:197], v[202:203], v[196:197]
	v_pk_fma_f32 v[144:145], v[140:141], v[144:145], v[198:199]
	v_pk_mul_f32 v[198:199], v[66:67], v[172:173] op_sel_hi:[1,0]
	v_pk_fma_f32 v[142:143], v[142:143], v[136:137], v[144:145]
	v_pk_mul_f32 v[144:145], v[68:69], v[172:173] op_sel_hi:[1,0]
	v_pk_mul_f32 v[142:143], v[200:201], v[142:143]
	v_cvt_pk_bf16_f32 v154, v198, v199
	v_cvt_pk_bf16_f32 v195, v144, v145
	v_cvt_pk_bf16_f32 v144, v196, v197
	v_cvt_pk_bf16_f32 v142, v142, v143
	v_cndmask_b32_e32 v143, v195, v142, vcc
	v_cndmask_b32_e32 v145, v154, v144, vcc
	ds_bpermute_b32 v196, v181, v145
	ds_bpermute_b32 v143, v181, v143
	v_pk_mul_f32 v[200:201], v[58:59], v[50:51]
	v_pk_mul_f32 v[204:205], v[62:63], v[170:171] op_sel_hi:[1,0]
	s_waitcnt lgkmcnt(1)
	v_cndmask_b32_e32 v144, v144, v196, vcc
	s_waitcnt lgkmcnt(0)
	v_cndmask_b32_e32 v145, v142, v143, vcc
	v_cndmask_b32_e32 v142, v196, v154, vcc
	v_add_co_u32_e64 v196, s[8:9], s8, v192
	v_cndmask_b32_e32 v143, v143, v195, vcc
	s_nop 0
	v_addc_co_u32_e64 v197, s[8:9], 0, v193, s[8:9]
	global_store_dwordx4 v[196:197], v[142:145], off
	v_lshl_add_u32 v154, v183, 2, s77
	ds_read_b128 v[142:145], v154 offset:512
	ds_read_b128 v[196:199], v154 offset:768
	v_mul_f32_e32 v154, v170, v170
	v_pk_mul_f32 v[200:201], v[200:201], v[154:155] op_sel_hi:[1,0]
	s_waitcnt lgkmcnt(0)
	v_cndmask_b32_e64 v183, v142, v196, s[6:7]
	v_cndmask_b32_e64 v195, v143, v197, s[6:7]
	v_mov_b32_dpp v207, v200 row_ror:2 row_mask:0xf bank_mask:0xf bound_ctrl:1
	v_mov_b32_dpp v209, v201 row_ror:2 row_mask:0xf bank_mask:0xf bound_ctrl:1
	v_mov_b32_dpp v206, v200 row_ror:1 row_mask:0xf bank_mask:0xf bound_ctrl:1
	v_mov_b32_dpp v208, v201 row_ror:1 row_mask:0xf bank_mask:0xf bound_ctrl:1
	v_cndmask_b32_e64 v203, v195, v209, s[0:1]
	v_cndmask_b32_e64 v202, v183, v207, s[0:1]
	v_cndmask_b32_e64 v197, v197, v208, s[2:3]
	v_cndmask_b32_e64 v196, v196, v206, s[2:3]
	v_pk_mul_f32 v[202:203], v[130:131], v[202:203]
	v_pk_mul_f32 v[142:143], v[60:61], v[52:53]
	v_pk_fma_f32 v[196:197], v[138:139], v[196:197], v[202:203]
	v_pk_mul_f32 v[142:143], v[142:143], v[154:155] op_sel_hi:[1,0]
	v_pk_fma_f32 v[196:197], v[200:201], v[134:135], v[196:197]
	v_cndmask_b32_e64 v183, v144, v198, s[6:7]
	v_pk_mul_f32 v[196:197], v[204:205], v[196:197]
	v_cndmask_b32_e64 v195, v145, v199, s[6:7]
	v_mov_b32_dpp v154, v142 row_ror:1 row_mask:0xf bank_mask:0xf bound_ctrl:1
	v_mov_b32_dpp v204, v142 row_ror:2 row_mask:0xf bank_mask:0xf bound_ctrl:1
	v_mov_b32_dpp v205, v143 row_ror:1 row_mask:0xf bank_mask:0xf bound_ctrl:1
	v_mov_b32_dpp v210, v143 row_ror:2 row_mask:0xf bank_mask:0xf bound_ctrl:1
	v_cndmask_b32_e64 v145, v199, v205, s[2:3]
	v_cndmask_b32_e64 v144, v198, v154, s[2:3]
	v_cndmask_b32_e64 v199, v195, v210, s[0:1]
	v_cndmask_b32_e64 v198, v183, v204, s[0:1]
	v_pk_mul_f32 v[198:199], v[132:133], v[198:199]
	v_pk_mul_f32 v[200:201], v[64:65], v[170:171] op_sel_hi:[1,0]
	v_pk_fma_f32 v[144:145], v[140:141], v[144:145], v[198:199]
	v_pk_mul_f32 v[198:199], v[42:43], v[170:171] op_sel_hi:[1,0]
	v_pk_fma_f32 v[142:143], v[142:143], v[136:137], v[144:145]
	v_pk_mul_f32 v[144:145], v[44:45], v[170:171] op_sel_hi:[1,0]
	v_pk_mul_f32 v[142:143], v[200:201], v[142:143]
	v_cvt_pk_bf16_f32 v183, v198, v199
	v_cvt_pk_bf16_f32 v195, v144, v145
	v_cvt_pk_bf16_f32 v144, v196, v197
	v_cvt_pk_bf16_f32 v142, v142, v143
	v_cndmask_b32_e32 v143, v195, v142, vcc
	v_cndmask_b32_e32 v145, v183, v144, vcc
	ds_bpermute_b32 v196, v181, v145
	ds_bpermute_b32 v143, v181, v143
	s_mov_b32 s6, 0x80000
	v_pk_mul_f32 v[202:203], v[54:55], v[168:169] op_sel_hi:[1,0]
	s_waitcnt lgkmcnt(1)
	v_cndmask_b32_e32 v144, v144, v196, vcc
	s_waitcnt lgkmcnt(0)
	v_cndmask_b32_e32 v145, v142, v143, vcc
	v_cndmask_b32_e32 v142, v196, v183, vcc
	v_add_co_u32_e64 v196, s[6:7], s6, v192
	v_cndmask_b32_e32 v143, v143, v195, vcc
	s_nop 0
	v_addc_co_u32_e64 v197, s[6:7], 0, v193, s[6:7]
	global_store_dwordx4 v[196:197], v[142:145], off
	v_pk_mul_f32 v[196:197], v[46:47], v[34:35]
	s_mov_b32 s6, 0x90000
	v_mul_f32_e32 v142, v168, v168
	v_pk_mul_f32 v[196:197], v[196:197], v[142:143] op_sel_hi:[1,0]
	v_pk_mul_f32 v[144:145], v[48:49], v[36:37]
	s_nop 0
	v_mov_b32_dpp v195, v196 row_ror:2 row_mask:0xf bank_mask:0xf bound_ctrl:1
	v_mov_b32_dpp v212, v197 row_ror:2 row_mask:0xf bank_mask:0xf bound_ctrl:1
	v_mov_b32_dpp v183, v196 row_ror:1 row_mask:0xf bank_mask:0xf bound_ctrl:1
	v_mov_b32_dpp v211, v197 row_ror:1 row_mask:0xf bank_mask:0xf bound_ctrl:1
	v_cndmask_b32_e64 v201, v209, v212, s[0:1]
	v_cndmask_b32_e64 v200, v207, v195, s[0:1]
	v_cndmask_b32_e64 v199, v208, v211, s[2:3]
	v_cndmask_b32_e64 v198, v206, v183, s[2:3]
	v_pk_mul_f32 v[200:201], v[130:131], v[200:201]
	v_pk_mul_f32 v[142:143], v[144:145], v[142:143] op_sel_hi:[1,0]
	v_pk_fma_f32 v[198:199], v[138:139], v[198:199], v[200:201]
	v_pk_mul_f32 v[200:201], v[56:57], v[168:169] op_sel_hi:[1,0]
	v_mov_b32_dpp v207, v142 row_ror:2 row_mask:0xf bank_mask:0xf bound_ctrl:1
	v_mov_b32_dpp v209, v143 row_ror:2 row_mask:0xf bank_mask:0xf bound_ctrl:1
	v_pk_fma_f32 v[196:197], v[196:197], v[134:135], v[198:199]
	v_mov_b32_dpp v206, v142 row_ror:1 row_mask:0xf bank_mask:0xf bound_ctrl:1
	v_mov_b32_dpp v208, v143 row_ror:1 row_mask:0xf bank_mask:0xf bound_ctrl:1
	v_cndmask_b32_e64 v199, v210, v209, s[0:1]
	v_cndmask_b32_e64 v198, v204, v207, s[0:1]
	v_cndmask_b32_e64 v145, v205, v208, s[2:3]
	v_cndmask_b32_e64 v144, v154, v206, s[2:3]
	v_pk_mul_f32 v[198:199], v[132:133], v[198:199]
	v_pk_mul_f32 v[196:197], v[202:203], v[196:197]
	v_pk_fma_f32 v[144:145], v[140:141], v[144:145], v[198:199]
	v_pk_mul_f32 v[198:199], v[26:27], v[168:169] op_sel_hi:[1,0]
	v_pk_fma_f32 v[142:143], v[142:143], v[136:137], v[144:145]
	v_pk_mul_f32 v[144:145], v[28:29], v[168:169] op_sel_hi:[1,0]
	v_pk_mul_f32 v[142:143], v[200:201], v[142:143]
	v_cvt_pk_bf16_f32 v154, v198, v199
	v_cvt_pk_bf16_f32 v198, v144, v145
	v_cvt_pk_bf16_f32 v144, v196, v197
	v_cvt_pk_bf16_f32 v142, v142, v143
	v_cndmask_b32_e32 v143, v198, v142, vcc
	v_cndmask_b32_e32 v145, v154, v144, vcc
	ds_bpermute_b32 v196, v181, v145
	ds_bpermute_b32 v143, v181, v143
	v_pk_mul_f32 v[202:203], v[38:39], v[166:167] op_sel_hi:[1,0]
	s_waitcnt lgkmcnt(1)
	v_cndmask_b32_e32 v144, v144, v196, vcc
	s_waitcnt lgkmcnt(0)
	v_cndmask_b32_e32 v145, v142, v143, vcc
	v_cndmask_b32_e32 v142, v196, v154, vcc
	v_add_co_u32_e64 v196, s[6:7], s6, v192
	v_cndmask_b32_e32 v143, v143, v198, vcc
	s_nop 0
	v_addc_co_u32_e64 v197, s[6:7], 0, v193, s[6:7]
	global_store_dwordx4 v[196:197], v[142:145], off
	v_pk_mul_f32 v[196:197], v[30:31], v[18:19]
	s_mov_b32 s6, 0xa0000
	v_mul_f32_e32 v142, v166, v166
	v_pk_mul_f32 v[196:197], v[196:197], v[142:143] op_sel_hi:[1,0]
	v_pk_mul_f32 v[144:145], v[32:33], v[20:21]
	s_nop 0
	v_mov_b32_dpp v204, v196 row_ror:2 row_mask:0xf bank_mask:0xf bound_ctrl:1
	v_mov_b32_dpp v210, v197 row_ror:2 row_mask:0xf bank_mask:0xf bound_ctrl:1
	v_mov_b32_dpp v154, v196 row_ror:1 row_mask:0xf bank_mask:0xf bound_ctrl:1
	v_mov_b32_dpp v205, v197 row_ror:1 row_mask:0xf bank_mask:0xf bound_ctrl:1
	v_cndmask_b32_e64 v201, v212, v210, s[0:1]
	v_cndmask_b32_e64 v200, v195, v204, s[0:1]
	v_cndmask_b32_e64 v199, v211, v205, s[2:3]
	v_cndmask_b32_e64 v198, v183, v154, s[2:3]
	v_pk_mul_f32 v[200:201], v[130:131], v[200:201]
	v_pk_mul_f32 v[142:143], v[144:145], v[142:143] op_sel_hi:[1,0]
	v_pk_fma_f32 v[198:199], v[138:139], v[198:199], v[200:201]
	v_pk_mul_f32 v[200:201], v[40:41], v[166:167] op_sel_hi:[1,0]
	v_pk_fma_f32 v[196:197], v[196:197], v[134:135], v[198:199]
	v_mov_b32_dpp v195, v142 row_ror:2 row_mask:0xf bank_mask:0xf bound_ctrl:1
	v_pk_mul_f32 v[196:197], v[202:203], v[196:197]
	v_mov_b32_dpp v203, v143 row_ror:2 row_mask:0xf bank_mask:0xf bound_ctrl:1
	v_mov_b32_dpp v183, v142 row_ror:1 row_mask:0xf bank_mask:0xf bound_ctrl:1
	v_mov_b32_dpp v202, v143 row_ror:1 row_mask:0xf bank_mask:0xf bound_ctrl:1
	v_cndmask_b32_e64 v199, v209, v203, s[0:1]
	v_cndmask_b32_e64 v198, v207, v195, s[0:1]
	v_cndmask_b32_e64 v145, v208, v202, s[2:3]
	v_cndmask_b32_e64 v144, v206, v183, s[2:3]
	v_pk_mul_f32 v[198:199], v[132:133], v[198:199]
	s_nop 0
	v_pk_fma_f32 v[144:145], v[140:141], v[144:145], v[198:199]
	v_pk_mul_f32 v[198:199], v[10:11], v[166:167] op_sel_hi:[1,0]
	v_pk_fma_f32 v[142:143], v[142:143], v[136:137], v[144:145]
	v_pk_mul_f32 v[144:145], v[12:13], v[166:167] op_sel_hi:[1,0]
	v_pk_mul_f32 v[142:143], v[200:201], v[142:143]
	v_cvt_pk_bf16_f32 v198, v198, v199
	v_cvt_pk_bf16_f32 v199, v144, v145
	v_cvt_pk_bf16_f32 v144, v196, v197
	v_cvt_pk_bf16_f32 v142, v142, v143
	v_cndmask_b32_e32 v143, v199, v142, vcc
	v_cndmask_b32_e32 v145, v198, v144, vcc
	ds_bpermute_b32 v196, v181, v145
	ds_bpermute_b32 v143, v181, v143
	s_waitcnt lgkmcnt(1)
	v_cndmask_b32_e32 v144, v144, v196, vcc
	s_waitcnt lgkmcnt(0)
	v_cndmask_b32_e32 v145, v142, v143, vcc
	v_cndmask_b32_e32 v142, v196, v198, vcc
	v_add_co_u32_e64 v196, s[6:7], s6, v192
	v_cndmask_b32_e32 v143, v143, v199, vcc
	s_nop 0
	v_addc_co_u32_e64 v197, s[6:7], 0, v193, s[6:7]
	global_store_dwordx4 v[196:197], v[142:145], off
	v_pk_mul_f32 v[198:199], v[22:23], v[164:165] op_sel_hi:[1,0]
	s_nop 0
	v_pk_mul_f32 v[144:145], v[190:191], v[188:189] op_sel_hi:[1,0]
	v_pk_mul_f32 v[142:143], v[16:17], v[8:9]
	s_nop 0
	v_mov_b32_dpp v196, v144 row_ror:2 row_mask:0xf bank_mask:0xf bound_ctrl:1
	v_mov_b32_dpp v197, v145 row_ror:2 row_mask:0xf bank_mask:0xf bound_ctrl:1
	v_mov_b32_dpp v190, v144 row_ror:1 row_mask:0xf bank_mask:0xf bound_ctrl:1
	v_mov_b32_dpp v191, v145 row_ror:1 row_mask:0xf bank_mask:0xf bound_ctrl:1
	v_cndmask_b32_e64 v197, v210, v197, s[0:1]
	v_cndmask_b32_e64 v196, v204, v196, s[0:1]
	v_cndmask_b32_e64 v191, v205, v191, s[2:3]
	v_cndmask_b32_e64 v190, v154, v190, s[2:3]
	v_pk_mul_f32 v[196:197], v[130:131], v[196:197]
	v_pk_mul_f32 v[142:143], v[142:143], v[188:189] op_sel_hi:[1,0]
	v_pk_fma_f32 v[190:191], v[138:139], v[190:191], v[196:197]
	s_nop 0
	v_mov_b32_dpp v188, v142 row_ror:2 row_mask:0xf bank_mask:0xf bound_ctrl:1
	v_mov_b32_dpp v196, v143 row_ror:2 row_mask:0xf bank_mask:0xf bound_ctrl:1
	v_pk_fma_f32 v[144:145], v[144:145], v[134:135], v[190:191]
	v_mov_b32_dpp v154, v142 row_ror:1 row_mask:0xf bank_mask:0xf bound_ctrl:1
	v_mov_b32_dpp v190, v143 row_ror:1 row_mask:0xf bank_mask:0xf bound_ctrl:1
	v_cndmask_b32_e64 v197, v203, v196, s[0:1]
	v_cndmask_b32_e64 v196, v195, v188, s[0:1]
	v_cndmask_b32_e64 v191, v202, v190, s[2:3]
	v_cndmask_b32_e64 v190, v183, v154, s[2:3]
	v_pk_mul_f32 v[196:197], v[132:133], v[196:197]
	v_pk_mul_f32 v[144:145], v[198:199], v[144:145]
	v_pk_fma_f32 v[190:191], v[140:141], v[190:191], v[196:197]
	v_pk_mul_f32 v[198:199], v[24:25], v[164:165] op_sel_hi:[1,0]
	v_pk_fma_f32 v[142:143], v[142:143], v[136:137], v[190:191]
	v_pk_mul_f32 v[190:191], v[4:5], v[164:165] op_sel_hi:[1,0]
	v_pk_mul_f32 v[142:143], v[198:199], v[142:143]
	v_pk_mul_f32 v[196:197], v[2:3], v[164:165] op_sel_hi:[1,0]
	v_cvt_pk_bf16_f32 v183, v190, v191
	v_cvt_pk_bf16_f32 v154, v196, v197
	v_cvt_pk_bf16_f32 v144, v144, v145
	v_cvt_pk_bf16_f32 v142, v142, v143
	v_cndmask_b32_e32 v143, v183, v142, vcc
	v_cndmask_b32_e32 v145, v154, v144, vcc
	ds_bpermute_b32 v188, v181, v145
	ds_bpermute_b32 v143, v181, v143
	s_mov_b64 s[2:3], 0
	s_waitcnt lgkmcnt(1)
	v_cndmask_b32_e32 v144, v144, v188, vcc
	s_waitcnt lgkmcnt(0)
	v_cndmask_b32_e32 v145, v142, v143, vcc
	v_cndmask_b32_e32 v142, v188, v154, vcc
	v_cndmask_b32_e32 v143, v143, v183, vcc
	v_add_co_u32_e32 v190, vcc, 0xb0000, v192
	s_nop 1
	v_addc_co_u32_e32 v191, vcc, 0, v193, vcc
	global_store_dwordx4 v[190:191], v[142:145], off

.LBB0_226:
	s_andn2_b64 vcc, exec, s[2:3]
	s_cbranch_vccnz .LBB0_204
	s_lshl_b32 s0, s70, 9
	s_add_u32 s0, s61, s0
	v_lshlrev_b32_e32 v130, 3, v194
	s_addc_u32 s1, s97, 0
	v_ashrrev_i32_e32 v131, 31, v130
	v_lshl_add_u64 v[130:131], v[130:131], 1, s[0:1]
	s_mov_b64 s[0:1], 0x4210400
	v_lshl_add_u64 v[130:131], v[130:131], 0, s[0:1]
	v_pk_mul_f32 v[128:129], v[128:129], v[178:179] op_sel_hi:[1,0]
	v_pk_mul_f32 v[126:127], v[126:127], v[178:179] op_sel_hi:[1,0]
	v_pk_mul_f32 v[134:135], v[124:125], v[178:179] op_sel_hi:[1,0]
	v_pk_mul_f32 v[124:125], v[122:123], v[178:179] op_sel_hi:[1,0]
	v_mad_i64_i32 v[132:133], s[0:1], v180, s69, v[130:131]
	v_cvt_pk_bf16_f32 v122, v126, v127
	v_cvt_pk_bf16_f32 v123, v128, v129
	v_cvt_pk_bf16_f32 v124, v124, v125
	v_cvt_pk_bf16_f32 v125, v134, v135
	global_store_dwordx4 v[132:133], v[122:125], off
	v_pk_mul_f32 v[116:117], v[116:117], v[178:179] op_sel_hi:[1,0]
	v_pk_mul_f32 v[114:115], v[114:115], v[178:179] op_sel_hi:[1,0]
	v_pk_mul_f32 v[122:123], v[108:109], v[178:179] op_sel_hi:[1,0]
	v_pk_mul_f32 v[108:109], v[106:107], v[178:179] op_sel_hi:[1,0]
	v_cvt_pk_bf16_f32 v106, v114, v115
	v_cvt_pk_bf16_f32 v107, v116, v117
	v_cvt_pk_bf16_f32 v108, v108, v109
	v_cvt_pk_bf16_f32 v109, v122, v123
	v_add_u32_e32 v136, 16, v180
	global_store_dwordx4 v[132:133], v[106:109], off offset:256
	v_pk_mul_f32 v[112:113], v[112:113], v[176:177] op_sel_hi:[1,0]
	v_pk_mul_f32 v[110:111], v[110:111], v[176:177] op_sel_hi:[1,0]
	v_pk_mul_f32 v[108:109], v[120:121], v[176:177] op_sel_hi:[1,0]
	v_pk_mul_f32 v[106:107], v[118:119], v[176:177] op_sel_hi:[1,0]
	v_mad_i64_i32 v[114:115], s[0:1], v136, s69, v[130:131]
	v_cvt_pk_bf16_f32 v106, v106, v107
	v_cvt_pk_bf16_f32 v107, v108, v109
	v_cvt_pk_bf16_f32 v108, v110, v111
	v_cvt_pk_bf16_f32 v109, v112, v113
	global_store_dwordx4 v[114:115], v[106:109], off
	v_pk_mul_f32 v[100:101], v[100:101], v[176:177] op_sel_hi:[1,0]
	v_pk_mul_f32 v[98:99], v[98:99], v[176:177] op_sel_hi:[1,0]
	v_pk_mul_f32 v[106:107], v[92:93], v[176:177] op_sel_hi:[1,0]
	v_pk_mul_f32 v[92:93], v[90:91], v[176:177] op_sel_hi:[1,0]
	v_cvt_pk_bf16_f32 v90, v98, v99
	v_cvt_pk_bf16_f32 v91, v100, v101
	v_cvt_pk_bf16_f32 v92, v92, v93
	v_cvt_pk_bf16_f32 v93, v106, v107
	v_add_u32_e32 v137, 32, v180
	global_store_dwordx4 v[114:115], v[90:93], off offset:256
	v_pk_mul_f32 v[96:97], v[96:97], v[174:175] op_sel_hi:[1,0]
	v_pk_mul_f32 v[94:95], v[94:95], v[174:175] op_sel_hi:[1,0]
	v_pk_mul_f32 v[92:93], v[104:105], v[174:175] op_sel_hi:[1,0]
	v_pk_mul_f32 v[90:91], v[102:103], v[174:175] op_sel_hi:[1,0]
	v_mad_i64_i32 v[98:99], s[0:1], v137, s69, v[130:131]
	v_cvt_pk_bf16_f32 v90, v90, v91
	v_cvt_pk_bf16_f32 v91, v92, v93
	v_cvt_pk_bf16_f32 v92, v94, v95
	v_cvt_pk_bf16_f32 v93, v96, v97
	global_store_dwordx4 v[98:99], v[90:93], off
	v_pk_mul_f32 v[84:85], v[84:85], v[174:175] op_sel_hi:[1,0]
	v_pk_mul_f32 v[82:83], v[82:83], v[174:175] op_sel_hi:[1,0]
	v_pk_mul_f32 v[90:91], v[76:77], v[174:175] op_sel_hi:[1,0]
	v_pk_mul_f32 v[76:77], v[74:75], v[174:175] op_sel_hi:[1,0]
	v_cvt_pk_bf16_f32 v74, v82, v83
	v_cvt_pk_bf16_f32 v75, v84, v85
	v_cvt_pk_bf16_f32 v76, v76, v77
	v_cvt_pk_bf16_f32 v77, v90, v91
	v_add_u32_e32 v138, 48, v180
	global_store_dwordx4 v[98:99], v[74:77], off offset:256
	v_pk_mul_f32 v[80:81], v[80:81], v[172:173] op_sel_hi:[1,0]
	v_pk_mul_f32 v[78:79], v[78:79], v[172:173] op_sel_hi:[1,0]
	v_pk_mul_f32 v[76:77], v[88:89], v[172:173] op_sel_hi:[1,0]
	v_pk_mul_f32 v[74:75], v[86:87], v[172:173] op_sel_hi:[1,0]
	v_mad_i64_i32 v[82:83], s[0:1], v138, s69, v[130:131]
	v_cvt_pk_bf16_f32 v74, v74, v75
	v_cvt_pk_bf16_f32 v75, v76, v77
	v_cvt_pk_bf16_f32 v76, v78, v79
	v_cvt_pk_bf16_f32 v77, v80, v81
	global_store_dwordx4 v[82:83], v[74:77], off
	v_pk_mul_f32 v[72:73], v[72:73], v[172:173] op_sel_hi:[1,0]
	v_pk_mul_f32 v[70:71], v[70:71], v[172:173] op_sel_hi:[1,0]
	v_pk_mul_f32 v[74:75], v[68:69], v[172:173] op_sel_hi:[1,0]
	v_pk_mul_f32 v[68:69], v[66:67], v[172:173] op_sel_hi:[1,0]
	v_cvt_pk_bf16_f32 v66, v70, v71
	v_cvt_pk_bf16_f32 v67, v72, v73
	v_cvt_pk_bf16_f32 v68, v68, v69
	v_cvt_pk_bf16_f32 v69, v74, v75
	v_add_u32_e32 v139, 0x80, v180
	global_store_dwordx4 v[82:83], v[66:69], off offset:256
	v_pk_mul_f32 v[64:65], v[64:65], v[170:171] op_sel_hi:[1,0]
	v_pk_mul_f32 v[62:63], v[62:63], v[170:171] op_sel_hi:[1,0]
	v_pk_mul_f32 v[68:69], v[60:61], v[170:171] op_sel_hi:[1,0]
	v_pk_mul_f32 v[60:61], v[58:59], v[170:171] op_sel_hi:[1,0]
	v_mad_i64_i32 v[66:67], s[0:1], v139, s69, v[130:131]
	v_cvt_pk_bf16_f32 v58, v62, v63
	v_cvt_pk_bf16_f32 v59, v64, v65
	v_cvt_pk_bf16_f32 v60, v60, v61
	v_cvt_pk_bf16_f32 v61, v68, v69
	global_store_dwordx4 v[66:67], v[58:61], off
	v_pk_mul_f32 v[52:53], v[52:53], v[170:171] op_sel_hi:[1,0]
	v_pk_mul_f32 v[50:51], v[50:51], v[170:171] op_sel_hi:[1,0]
	v_pk_mul_f32 v[58:59], v[44:45], v[170:171] op_sel_hi:[1,0]
	v_pk_mul_f32 v[44:45], v[42:43], v[170:171] op_sel_hi:[1,0]
	v_cvt_pk_bf16_f32 v42, v50, v51
	v_cvt_pk_bf16_f32 v43, v52, v53
	v_cvt_pk_bf16_f32 v44, v44, v45
	v_cvt_pk_bf16_f32 v45, v58, v59
	v_add_u32_e32 v140, 0x90, v180
	global_store_dwordx4 v[66:67], v[42:45], off offset:256
	v_pk_mul_f32 v[48:49], v[48:49], v[168:169] op_sel_hi:[1,0]
	v_pk_mul_f32 v[46:47], v[46:47], v[168:169] op_sel_hi:[1,0]
	v_pk_mul_f32 v[44:45], v[56:57], v[168:169] op_sel_hi:[1,0]
	v_pk_mul_f32 v[42:43], v[54:55], v[168:169] op_sel_hi:[1,0]
	v_mad_i64_i32 v[50:51], s[0:1], v140, s69, v[130:131]
	v_cvt_pk_bf16_f32 v42, v42, v43
	v_cvt_pk_bf16_f32 v43, v44, v45
	v_cvt_pk_bf16_f32 v44, v46, v47
	v_cvt_pk_bf16_f32 v45, v48, v49
	global_store_dwordx4 v[50:51], v[42:45], off
	v_pk_mul_f32 v[36:37], v[36:37], v[168:169] op_sel_hi:[1,0]
	v_pk_mul_f32 v[34:35], v[34:35], v[168:169] op_sel_hi:[1,0]
	v_pk_mul_f32 v[42:43], v[28:29], v[168:169] op_sel_hi:[1,0]
	v_pk_mul_f32 v[28:29], v[26:27], v[168:169] op_sel_hi:[1,0]
	v_cvt_pk_bf16_f32 v26, v34, v35
	v_cvt_pk_bf16_f32 v27, v36, v37
	v_cvt_pk_bf16_f32 v28, v28, v29
	v_cvt_pk_bf16_f32 v29, v42, v43
	v_add_u32_e32 v141, 0xa0, v180
	global_store_dwordx4 v[50:51], v[26:29], off offset:256
	v_pk_mul_f32 v[32:33], v[32:33], v[166:167] op_sel_hi:[1,0]
	v_pk_mul_f32 v[30:31], v[30:31], v[166:167] op_sel_hi:[1,0]
	v_pk_mul_f32 v[28:29], v[40:41], v[166:167] op_sel_hi:[1,0]
	v_pk_mul_f32 v[26:27], v[38:39], v[166:167] op_sel_hi:[1,0]
	v_mad_i64_i32 v[34:35], s[0:1], v141, s69, v[130:131]
	v_cvt_pk_bf16_f32 v26, v26, v27
	v_cvt_pk_bf16_f32 v27, v28, v29
	v_cvt_pk_bf16_f32 v28, v30, v31
	v_cvt_pk_bf16_f32 v29, v32, v33
	global_store_dwordx4 v[34:35], v[26:29], off
	v_pk_mul_f32 v[20:21], v[20:21], v[166:167] op_sel_hi:[1,0]
	v_pk_mul_f32 v[18:19], v[18:19], v[166:167] op_sel_hi:[1,0]
	v_pk_mul_f32 v[26:27], v[12:13], v[166:167] op_sel_hi:[1,0]
	v_pk_mul_f32 v[12:13], v[10:11], v[166:167] op_sel_hi:[1,0]
	v_cvt_pk_bf16_f32 v10, v18, v19
	v_cvt_pk_bf16_f32 v11, v20, v21
	v_cvt_pk_bf16_f32 v12, v12, v13
	v_cvt_pk_bf16_f32 v13, v26, v27
	v_add_u32_e32 v142, 0xb0, v180
	global_store_dwordx4 v[34:35], v[10:13], off offset:256
	v_pk_mul_f32 v[16:17], v[16:17], v[164:165] op_sel_hi:[1,0]
	v_pk_mul_f32 v[14:15], v[14:15], v[164:165] op_sel_hi:[1,0]
	v_pk_mul_f32 v[12:13], v[24:25], v[164:165] op_sel_hi:[1,0]
	v_pk_mul_f32 v[10:11], v[22:23], v[164:165] op_sel_hi:[1,0]
	v_mad_i64_i32 v[18:19], s[0:1], v142, s69, v[130:131]
	v_cvt_pk_bf16_f32 v10, v10, v11
	v_cvt_pk_bf16_f32 v11, v12, v13
	v_cvt_pk_bf16_f32 v12, v14, v15
	v_cvt_pk_bf16_f32 v13, v16, v17
	global_store_dwordx4 v[18:19], v[10:13], off
	v_pk_mul_f32 v[8:9], v[8:9], v[164:165] op_sel_hi:[1,0]
	v_pk_mul_f32 v[6:7], v[6:7], v[164:165] op_sel_hi:[1,0]
	v_pk_mul_f32 v[10:11], v[4:5], v[164:165] op_sel_hi:[1,0]
	v_pk_mul_f32 v[4:5], v[2:3], v[164:165] op_sel_hi:[1,0]
	v_cvt_pk_bf16_f32 v2, v6, v7
	v_cvt_pk_bf16_f32 v3, v8, v9
	v_cvt_pk_bf16_f32 v4, v4, v5
	v_cvt_pk_bf16_f32 v5, v10, v11
	global_store_dwordx4 v[18:19], v[2:5], off offset:256
	s_branch .LBB0_204

.Lpeel_p10_exit:
	s_and_b64 vcc, exec, s[0:1]
	s_cbranch_vccz .Lslab10_skip
	s_cmp_gt_i32 s82, 43
	s_cbranch_scc1 .Lslab10_skip
	s_lshl_b32 s100, s82, 6
	s_and_b32 s100, s100, 0xffffff00
	s_lshl_b32 s100, s100, 1
	s_and_b32 s98, s82, 3
	s_mul_i32 s98, s98, 0x160000
	s_add_u32 s98, s24, s98
	s_addc_u32 s99, s25, 0
	s_add_u32 s98, s98, s100
	s_addc_u32 s99, s99, 0
	s_add_i32 m0, s27, 0x10000
	s_nop 0
	global_load_lds_dwordx4 v130, s[98:99]
	s_add_i32 m0, s27, 0x12000
	s_nop 0
	global_load_lds_dwordx4 v132, s[98:99]
	s_add_u32 s98, s98, 0xb0000
	s_addc_u32 s99, s99, 0
	s_add_i32 m0, s27, 0x14000
	s_nop 0
	global_load_lds_dwordx4 v130, s[98:99]
	s_add_i32 m0, s27, 0x16000
	s_nop 0
	global_load_lds_dwordx4 v132, s[98:99]
	s_add_u32 s98, s94, s100
	s_addc_u32 s99, s95, 0
	s_add_u32 s98, s98, 0x9a12400
	s_addc_u32 s99, s99, 0
	s_mov_b32 m0, s27
	s_nop 0
	global_load_lds_dwordx4 v130, s[98:99]
	s_add_i32 m0, s27, 0x2000
	s_nop 0
	global_load_lds_dwordx4 v132, s[98:99]
	s_add_u32 s98, s98, 0xb0000
	s_addc_u32 s99, s99, 0
	s_add_i32 m0, s27, 0x4000
	s_nop 0
	global_load_lds_dwordx4 v130, s[98:99]
	s_add_i32 m0, s27, 0x6000
	s_nop 0
	global_load_lds_dwordx4 v132, s[98:99]

.LBB0_1202:
	s_cmp_gt_i32 s82, 43
	v_readfirstlane_b32 s4, v0
	s_cbranch_scc1 .LBB0_1208
	s_lshl_b32 s0, s82, 6
	s_and_b32 s0, s0, 0xffffff00
	s_lshr_b32 s8, s4, 6
	s_and_b32 s5, s82, 3
	s_ashr_i32 s1, s0, 31
	s_lshr_b32 s20, s4, 8
	s_lshl_b32 s19, s8, 10
	s_lshl_b64 s[0:1], s[0:1], 1
	s_mul_i32 s2, s5, 0x160000
	s_add_u32 s2, s24, s2
	s_addc_u32 s3, s25, 0
	s_add_u32 s2, s2, s0
	s_addc_u32 s3, s3, s1
	s_add_i32 s9, s19, 0
	s_add_i32 m0, s9, 0x10000
	v_mov_b32_e32 v131, 0
	s_add_i32 m0, s9, 0x12000
	s_add_u32 s12, s94, s0
	s_addc_u32 s13, s95, s1
	s_add_u32 s0, s12, 0x9a12400
	s_addc_u32 s1, s13, 0
	s_mov_b32 m0, s9
	s_add_i32 s18, s9, 0x2000
	s_mov_b32 m0, s18
	s_add_u32 s10, s2, 0xb0000
	s_addc_u32 s11, s3, 0
	s_add_i32 m0, s9, 0x14000
	v_mov_b32_e32 v133, v131
	s_add_i32 m0, s9, 0x16000
	s_add_u32 s12, s12, 0x9ac2400
	s_addc_u32 s13, s13, 0
	s_add_i32 s14, s9, 0x4000
	s_mov_b32 m0, s14
	s_add_i32 s15, s9, 0x6000
	s_mov_b32 m0, s15
	v_lshl_add_u64 v[34:35], s[2:3], 0, v[130:131]
	v_lshl_add_u64 v[36:37], s[2:3], 0, v[132:133]
	v_lshl_add_u64 v[32:33], s[0:1], 0, v[130:131]
	v_lshl_add_u64 v[30:31], s[0:1], 0, v[132:133]
	v_lshl_add_u64 v[28:29], s[10:11], 0, v[130:131]
	v_lshl_add_u64 v[26:27], s[10:11], 0, v[132:133]
	v_lshl_add_u64 v[22:23], s[12:13], 0, v[130:131]
	s_cmp_lg_u32 s20, 1
	v_lshl_add_u64 v[24:25], s[12:13], 0, v[132:133]
	s_cbranch_scc1 .LBB0_1205
	s_barrier
